# FoX tile loop: defer the forget-prefix load wait (was vmcnt(0) at loop head, exposing K/V prefetch latency on waves 0-1) to the LDS-store point; on top of P4 load hoist
# speedup vs baseline: 1.0072x; 1.0051x over previous
.LBB0_459:
	s_add_i32 s18, s39, s40
	s_add_i32 s19, s18, 31
	s_cmp_gt_i32 s19, s41
	s_cselect_b64 s[16:17], -1, 0
	s_cmp_le_i32 s19, s41
	s_cbranch_scc1 .LBB0_463
	s_add_i32 s18, s18, 30
	s_ashr_i32 s19, s18, 31
	s_lshl_b64 s[18:19], s[18:19], 7
	v_or_b32_e32 v0, s18, v132
	v_mad_u64_u32 v[36:37], s[58:59], v0, s49, v[142:143]
	v_mad_i32_i24 v37, s19, v166, v37
	v_add_co_u32_e32 v38, vcc, 0x70000, v36
	v_mad_u64_u32 v[40:41], s[58:59], v0, s49, v[144:145]
	s_nop 0
	v_addc_co_u32_e32 v39, vcc, 0, v37, vcc
	v_mad_i32_i24 v41, s19, v166, v41
	global_load_dwordx4 v[116:119], v[36:37], off
	global_load_dwordx4 v[124:127], v[40:41], off
	v_add_co_u32_e32 v36, vcc, 0x70000, v40
	s_nop 1
	v_addc_co_u32_e32 v37, vcc, 0, v41, vcc
	global_load_dwordx4 v[120:123], v[38:39], off
	global_load_dwordx4 v[128:131], v[36:37], off
	s_and_saveexec_b64 s[18:19], s[4:5]
	s_cbranch_execz .LBB0_462
	v_add_u32_e32 v36, s44, v168
	v_ashrrev_i32_e32 v37, 31, v36
	v_lshl_add_u64 v[36:37], v[36:37], 2, s[14:15]
	global_load_dword v198, v[36:37], off

.LBB0_478:
	s_mul_i32 s16, s45, 0x4800
	v_add_u32_e32 v36, s16, v155
	s_waitcnt vmcnt(3)
	ds_write_b128 v36, v[116:119]
	s_waitcnt vmcnt(1)
	ds_write_b128 v36, v[120:123] offset:9216
	ds_write_b128 v36, v[124:127] offset:36864
	s_waitcnt vmcnt(0)
	ds_write_b128 v36, v[128:131] offset:46080
	s_and_saveexec_b64 s[16:17], s[4:5]
	v_lshl_add_u32 v36, s45, 9, v156
	v_sub_f32_e32 v137, v35, v198
	ds_write_b32 v36, v137
	s_or_b64 exec, exec, s[16:17]
